# grid barrier: last XCD leader bumps all XCD generation words directly (TOPGEN relay hop removed); other leaders wait on their own XCD word
# speedup vs baseline: 1.0043x; 1.0043x over previous
.LBB0_667:
	v_readlane_b32 s8, v254, 34
	s_add_u32 s29, s2, s8
	s_addc_u32 s28, s3, 0
	v_mov_b32_e32 v3, s29
	v_add_co_u32_e32 v4, vcc, 0x1000, v3
	v_mov_b32_e32 v3, s28
	s_nop 0
	v_addc_co_u32_e32 v5, vcc, 0, v3, vcc
	flat_atomic_add v4, v[4:5], v194 offset:1024 sc0
	v_cvt_f32_u32_e32 v3, v2
	v_sub_u32_e32 v5, 0, v2
	v_rcp_iflag_f32_e32 v3, v3
	s_nop 0
	v_mul_f32_e32 v3, 0x4f7ffffe, v3
	v_cvt_u32_f32_e32 v3, v3
	v_mul_lo_u32 v5, v5, v3
	v_mul_hi_u32 v5, v3, v5
	v_add_u32_e32 v3, v3, v5
	s_waitcnt vmcnt(0) lgkmcnt(0)
	v_mul_hi_u32 v3, v4, v3
	v_mul_lo_u32 v5, v3, v2
	v_sub_u32_e32 v5, v4, v5
	v_cmp_ge_u32_e32 vcc, v5, v2
	v_add_u32_e32 v6, 1, v3
	s_nop 0
	v_cndmask_b32_e32 v3, v3, v6, vcc
	v_sub_u32_e32 v6, v5, v2
	v_cndmask_b32_e32 v5, v5, v6, vcc
	v_cmp_ge_u32_e32 vcc, v5, v2
	v_add_u32_e32 v5, 1, v3
	v_add_u32_e32 v6, 1, v4
	v_cndmask_b32_e32 v3, v3, v5, vcc
	v_mov_b32_e32 v20, v3
	v_mad_u64_u32 v[4:5], s[8:9], v2, v3, v[2:3]
	v_cmp_ne_u32_e32 vcc, v6, v4
	s_and_saveexec_b64 s[8:9], vcc
	s_xor_b64 s[8:9], exec, s[8:9]
	s_cbranch_execz .LBB0_680
	v_mov_b32_e32 v0, s29
	v_add_co_u32_e32 v4, vcc, 0x2000, v0
	v_mov_b32_e32 v0, s28
	s_nop 0
	v_addc_co_u32_e32 v5, vcc, 0, v0, vcc
	flat_load_dword v0, v[4:5] offset:1024 sc1
	s_add_u32 s12, s29, 0x2400
	s_addc_u32 s13, s28, 0
	s_waitcnt vmcnt(0) lgkmcnt(0)
	v_cmp_eq_u32_e32 vcc, v0, v3
	s_and_saveexec_b64 s[10:11], vcc
	s_cbranch_execz .LBB0_679
	s_mov_b32 s30, 1
	s_mov_b64 s[14:15], 0
	s_branch .LBB0_671

.LBB0_680:
	s_andn2_saveexec_b64 s[8:9], s[8:9]
	s_cbranch_execz .LBB0_696
	v_mov_b32_e32 v2, s2
	v_add_co_u32_e32 v2, vcc, 0x3000, v2
	v_mov_b32_e32 v3, s3
	buffer_wbl2 sc1
	s_waitcnt vmcnt(0)
	v_addc_co_u32_e32 v3, vcc, 0, v3, vcc
	flat_atomic_add v2, v[2:3], v194 offset:1024 sc0
	v_cvt_f32_u32_e32 v3, v0
	v_sub_u32_e32 v4, 0, v0
	s_mov_b64 s[12:13], -1
	v_rcp_iflag_f32_e32 v3, v3
	s_nop 0
	v_mul_f32_e32 v3, 0x4f7ffffe, v3
	v_cvt_u32_f32_e32 v3, v3
	v_mul_lo_u32 v4, v4, v3
	v_mul_hi_u32 v4, v3, v4
	v_add_u32_e32 v3, v3, v4
	s_waitcnt vmcnt(0) lgkmcnt(0)
	v_mul_hi_u32 v3, v2, v3
	v_mul_lo_u32 v4, v3, v0
	v_sub_u32_e32 v4, v2, v4
	v_cmp_ge_u32_e32 vcc, v4, v0
	v_add_u32_e32 v5, 1, v3
	s_nop 0
	v_cndmask_b32_e32 v3, v3, v5, vcc
	v_sub_u32_e32 v5, v4, v0
	v_cndmask_b32_e32 v4, v4, v5, vcc
	v_cmp_ge_u32_e32 vcc, v4, v0
	v_add_u32_e32 v4, 1, v3
	v_add_u32_e32 v5, 1, v2
	v_cndmask_b32_e32 v4, v3, v4, vcc
	v_mad_u64_u32 v[2:3], s[8:9], v0, v4, v[0:1]
	s_add_u32 s8, s29, 0x2400
	s_addc_u32 s9, s28, 0
	v_cmp_ne_u32_e32 vcc, v5, v2
	v_mov_b32_e32 v4, v20
	v_mov_b64_e32 v[2:3], s[8:9]
	s_andn2_b64 s[10:11], exec, vcc
	s_and_saveexec_b64 s[14:15], s[10:11]
	s_cbranch_execz .Lxb_notlast
	s_add_u32 s16, s72, 0x2400
	s_addc_u32 s17, s73, 0
	v_mov_b32_e32 v6, s16
	v_mov_b32_e32 v7, s17
	s_mov_b64 s[12:13], 0
	flat_atomic_add v[6:7], v194
	flat_atomic_add v[6:7], v194 offset:256
	flat_atomic_add v[6:7], v194 offset:512
	flat_atomic_add v[6:7], v194 offset:768
	flat_atomic_add v[6:7], v194 offset:1024
	flat_atomic_add v[6:7], v194 offset:1280
	flat_atomic_add v[6:7], v194 offset:1536
	flat_atomic_add v[6:7], v194 offset:1792
	flat_atomic_add v[6:7], v194 offset:2048
	flat_atomic_add v[6:7], v194 offset:2304
	flat_atomic_add v[6:7], v194 offset:2560
	flat_atomic_add v[6:7], v194 offset:2816
	flat_atomic_add v[6:7], v194 offset:3072
	flat_atomic_add v[6:7], v194 offset:3328
	flat_atomic_add v[6:7], v194 offset:3584
	flat_atomic_add v[6:7], v194 offset:3840
.Lxb_notlast:
	s_mov_b64 exec, s[14:15]
	s_and_saveexec_b64 s[10:11], vcc
	s_cbranch_execz .LBB0_693
	v_mov_b64_e32 v[2:3], s[8:9]
	flat_load_dword v0, v[2:3] sc1
	s_mov_b64 s[16:17], 0
	s_waitcnt vmcnt(0) lgkmcnt(0)
	v_cmp_eq_u32_e32 vcc, v0, v4
	s_and_saveexec_b64 s[14:15], vcc
	s_cbranch_execz .LBB0_692
	s_add_u32 s12, s2, 0x200
	s_addc_u32 s13, s3, 0
	s_mov_b32 s26, 1
	s_mov_b64 s[2:3], 0
	s_branch .LBB0_685

.LBB0_695:
	s_or_b64 exec, exec, s[2:3]
	v_mov_b32_e32 v0, s29
	v_add_co_u32_e32 v2, vcc, 0x2000, v0
	v_mov_b32_e32 v0, s28
	s_nop 0
	v_addc_co_u32_e32 v3, vcc, 0, v0, vcc
	s_waitcnt vmcnt(0) lgkmcnt(0)
	buffer_inv sc1
	s_waitcnt vmcnt(0)
